# attention: waves 4-7 defer PV by one tile (3-slot V ring, one barrier per tile), waves 0-3 unchanged order
# baseline (speedup 1.0000x reference)
.LBB0_987:
	v_add_f32_e32 v76, 0, v76
	v_add_f32_e32 v76, v77, v76
	v_add_f32_e32 v76, v78, v76
	v_add_f32_e32 v76, v79, v76
	v_add_f32_e32 v76, v80, v76
	v_add_f32_e32 v76, v81, v76
	v_add_f32_e32 v76, v82, v76
	v_add_f32_e32 v76, v83, v76
	v_add_f32_e32 v76, v84, v76
	v_add_f32_e32 v76, v85, v76
	v_add_f32_e32 v76, v86, v76
	v_add_f32_e32 v76, v87, v76
	v_add_f32_e32 v76, v88, v76
	v_add_f32_e32 v76, v89, v76
	v_add_f32_e32 v76, v90, v76
	v_add_f32_e32 v76, v91, v76
	v_add_f32_e32 v80, v156, v76
	v_fmamk_f32 v76, v112, 0x3dd53b94, v155
	v_exp_f32_e32 v76, v76
	v_fmamk_f32 v78, v113, 0x3dd53b94, v155
	v_exp_f32_e32 v78, v78
	v_fmamk_f32 v79, v114, 0x3dd53b94, v155
	v_exp_f32_e32 v79, v79
	v_fmamk_f32 v81, v115, 0x3dd53b94, v155
	v_exp_f32_e32 v82, v81
	v_fmamk_f32 v81, v116, 0x3dd53b94, v155
	v_add_f32_e32 v77, 0, v76
	v_exp_f32_e32 v83, v81
	v_fmamk_f32 v81, v117, 0x3dd53b94, v155
	v_add_f32_e32 v77, v78, v77
	v_exp_f32_e32 v84, v81
	v_fmamk_f32 v81, v118, 0x3dd53b94, v155
	v_add_f32_e32 v77, v79, v77
	v_exp_f32_e32 v85, v81
	v_fmamk_f32 v81, v119, 0x3dd53b94, v155
	v_add_f32_e32 v77, v82, v77
	v_exp_f32_e32 v86, v81
	v_fmamk_f32 v81, v120, 0x3dd53b94, v155
	v_add_f32_e32 v77, v83, v77
	v_exp_f32_e32 v87, v81
	v_fmamk_f32 v81, v121, 0x3dd53b94, v155
	v_add_f32_e32 v77, v84, v77
	v_exp_f32_e32 v88, v81
	v_fmamk_f32 v81, v122, 0x3dd53b94, v155
	v_add_f32_e32 v77, v85, v77
	v_exp_f32_e32 v89, v81
	v_fmamk_f32 v81, v123, 0x3dd53b94, v155
	v_add_f32_e32 v77, v86, v77
	v_exp_f32_e32 v90, v81
	v_fmamk_f32 v72, v72, 0x3dd53b94, v155
	v_add_f32_e32 v77, v87, v77
	v_exp_f32_e32 v91, v72
	v_fmamk_f32 v73, v73, 0x3dd53b94, v155
	v_add_f32_e32 v77, v88, v77
	v_exp_f32_e32 v92, v73
	v_fmamk_f32 v73, v74, 0x3dd53b94, v155
	v_add_f32_e32 v77, v89, v77
	v_exp_f32_e32 v93, v73
	v_fmamk_f32 v73, v75, 0x3dd53b94, v155
	v_add_f32_e32 v77, v90, v77
	v_exp_f32_e32 v75, v73
	v_add_f32_e32 v72, v91, v77
	v_add_f32_e32 v72, v92, v72
	v_add_f32_e32 v72, v93, v72
	v_add_f32_e32 v72, v75, v72
	v_add_f32_e32 v81, v154, v72
	v_cvt_pk_bf16_f32 v76, v76, v78
	v_cvt_pk_bf16_f32 v77, v79, v82
	v_cvt_pk_bf16_f32 v78, v83, v84
	v_cvt_pk_bf16_f32 v79, v85, v86
	v_cvt_pk_bf16_f32 v72, v87, v88
	v_cvt_pk_bf16_f32 v73, v89, v90
	v_add3_u32 v90, s2, v144, v202
	v_cvt_pk_bf16_f32 v74, v91, v92
	v_cvt_pk_bf16_f32 v75, v93, v75
	ds_read_b64 v[82:83], v90 offset:24576
	ds_read_b64 v[84:85], v90 offset:24608
	s_waitcnt lgkmcnt(0)
	v_mfma_f32_16x16x32_bf16 v[60:63], v[82:85], v[68:71], v[60:63]
	s_lshl_b32 s24, s24, 1
	v_mfma_f32_16x16x32_bf16 v[56:59], v[82:85], v[76:79], v[56:59]
	ds_read_b64 v[82:83], v90 offset:24640
	ds_read_b64 v[84:85], v90 offset:24672
	s_waitcnt lgkmcnt(0)
	v_mfma_f32_16x16x32_bf16 v[60:63], v[82:85], v[64:67], v[60:63]
	v_mfma_f32_16x16x32_bf16 v[56:59], v[82:85], v[72:75], v[56:59]
	ds_read_b64 v[82:83], v90 offset:26880
	ds_read_b64 v[84:85], v90 offset:26912
	s_waitcnt lgkmcnt(0)
	v_mfma_f32_16x16x32_bf16 v[52:55], v[82:85], v[68:71], v[52:55]
	v_mfma_f32_16x16x32_bf16 v[48:51], v[82:85], v[76:79], v[48:51]
	ds_read_b64 v[82:83], v90 offset:26944
	ds_read_b64 v[84:85], v90 offset:26976
	s_waitcnt lgkmcnt(0)
	v_mfma_f32_16x16x32_bf16 v[52:55], v[82:85], v[64:67], v[52:55]
	v_mfma_f32_16x16x32_bf16 v[48:51], v[82:85], v[72:75], v[48:51]
	ds_read_b64 v[82:83], v90 offset:29184
	ds_read_b64 v[84:85], v90 offset:29216
	s_waitcnt lgkmcnt(0)
	v_mfma_f32_16x16x32_bf16 v[44:47], v[82:85], v[68:71], v[44:47]
	v_mfma_f32_16x16x32_bf16 v[40:43], v[82:85], v[76:79], v[40:43]
	ds_read_b64 v[82:83], v90 offset:29248
	ds_read_b64 v[84:85], v90 offset:29280
	s_waitcnt lgkmcnt(0)
	v_mfma_f32_16x16x32_bf16 v[44:47], v[82:85], v[64:67], v[44:47]
	v_mfma_f32_16x16x32_bf16 v[40:43], v[82:85], v[72:75], v[40:43]
	ds_read_b64 v[82:83], v90 offset:31488
	ds_read_b64 v[84:85], v90 offset:31520
	s_waitcnt lgkmcnt(0)
	v_mfma_f32_16x16x32_bf16 v[36:39], v[82:85], v[68:71], v[36:39]
	v_mfma_f32_16x16x32_bf16 v[28:31], v[82:85], v[76:79], v[28:31]
	ds_read_b64 v[82:83], v90 offset:31552
	ds_read_b64 v[84:85], v90 offset:31584
	s_waitcnt lgkmcnt(0)
	v_mfma_f32_16x16x32_bf16 v[36:39], v[82:85], v[64:67], v[36:39]
	v_mfma_f32_16x16x32_bf16 v[28:31], v[82:85], v[72:75], v[28:31]
	ds_read_b64 v[82:83], v90 offset:33792
	ds_read_b64 v[84:85], v90 offset:33824
	ds_read_b64 v[86:87], v90 offset:33856
	ds_read_b64 v[88:89], v90 offset:33888
	s_waitcnt lgkmcnt(2)
	v_mfma_f32_16x16x32_bf16 v[24:27], v[82:85], v[68:71], v[24:27]
	v_mfma_f32_16x16x32_bf16 v[82:85], v[82:85], v[76:79], v[32:35]
	s_waitcnt lgkmcnt(0)
	v_mfma_f32_16x16x32_bf16 v[32:35], v[86:89], v[64:67], v[24:27]
	v_mfma_f32_16x16x32_bf16 v[24:27], v[86:89], v[72:75], v[82:85]
	s_nop 4
	ds_read_b64 v[82:83], v90 offset:36096
	ds_read_b64 v[84:85], v90 offset:36128
	ds_read_b64 v[86:87], v90 offset:36160
	ds_read_b64 v[88:89], v90 offset:36192
	s_waitcnt lgkmcnt(2)
	v_mfma_f32_16x16x32_bf16 v[16:19], v[82:85], v[68:71], v[16:19]
	v_mfma_f32_16x16x32_bf16 v[82:85], v[82:85], v[76:79], v[20:23]
	s_waitcnt lgkmcnt(0)
	v_mfma_f32_16x16x32_bf16 v[20:23], v[86:89], v[64:67], v[16:19]
	v_mfma_f32_16x16x32_bf16 v[16:19], v[86:89], v[72:75], v[82:85]
	s_nop 4
	ds_read_b64 v[82:83], v90 offset:38400
	ds_read_b64 v[84:85], v90 offset:38432
	ds_read_b64 v[86:87], v90 offset:38464
	ds_read_b64 v[88:89], v90 offset:38496
	s_waitcnt lgkmcnt(2)
	v_mfma_f32_16x16x32_bf16 v[8:11], v[82:85], v[68:71], v[8:11]
	v_mfma_f32_16x16x32_bf16 v[82:85], v[82:85], v[76:79], v[12:15]
	s_waitcnt lgkmcnt(0)
	v_mfma_f32_16x16x32_bf16 v[12:15], v[86:89], v[64:67], v[8:11]
	v_mfma_f32_16x16x32_bf16 v[8:11], v[86:89], v[72:75], v[82:85]
	s_nop 4
	ds_read_b64 v[82:83], v90 offset:40704
	ds_read_b64 v[84:85], v90 offset:40736
	s_waitcnt lgkmcnt(0)
	v_mfma_f32_16x16x32_bf16 v[0:3], v[82:85], v[68:71], v[0:3]
	ds_read_b64 v[68:69], v90 offset:40768
	ds_read_b64 v[70:71], v90 offset:40800
	v_mfma_f32_16x16x32_bf16 v[4:7], v[82:85], v[76:79], v[4:7]
	s_waitcnt vmcnt(0)
	s_waitcnt lgkmcnt(0)
	v_mfma_f32_16x16x32_bf16 v[64:67], v[68:71], v[64:67], v[0:3]
	s_barrier
	v_mfma_f32_16x16x32_bf16 v[0:3], v[68:71], v[72:75], v[4:7]
	s_nop 3
	v_and_b32_e32 v5, 64, v227
	v_xor_b32_e32 v4, 16, v227
	v_add_u32_e32 v5, 64, v5
	v_cmp_lt_i32_e32 vcc, v4, v5
	s_nop 1
	v_cndmask_b32_e32 v4, v227, v4, vcc
	v_lshlrev_b32_e32 v68, 2, v4
	ds_bpermute_b32 v6, v68, v80
	v_xor_b32_e32 v4, 32, v227
	v_cmp_lt_i32_e32 vcc, v4, v5
	s_waitcnt lgkmcnt(0)
	v_add_f32_e32 v6, v80, v6
	v_cndmask_b32_e32 v4, v227, v4, vcc
	v_lshlrev_b32_e32 v69, 2, v4
	ds_bpermute_b32 v7, v69, v6
	v_lshl_add_u64 v[4:5], v[148:149], 0, s[24:25]
	s_waitcnt lgkmcnt(0)
	v_add_f32_e32 v6, v6, v7
	v_div_scale_f32 v7, s[8:9], v6, v6, 1.0
	v_rcp_f32_e32 v70, v7
	s_nop 0
	v_fma_f32 v71, -v7, v70, 1.0
	v_fmac_f32_e32 v70, v71, v70
	v_div_scale_f32 v71, vcc, 1.0, v6, 1.0
	v_mul_f32_e32 v72, v71, v70
	v_fma_f32 v73, -v7, v72, v71
	v_fmac_f32_e32 v72, v73, v70
	v_fma_f32 v7, -v7, v72, v71
	v_div_fmas_f32 v7, v7, v70, v72
	v_div_fixup_f32 v70, v7, v6, 1.0
	v_lshlrev_b64 v[6:7], 11, v[152:153]
	v_mul_f32_e32 v60, v60, v70
	v_mul_f32_e32 v61, v61, v70
	v_lshl_add_u64 v[6:7], v[4:5], 0, v[6:7]
	v_cvt_pk_bf16_f32 v60, v60, v61
	v_mul_f32_e32 v61, v62, v70
	v_mul_f32_e32 v52, v52, v70
	v_mul_f32_e32 v53, v53, v70
	v_mul_f32_e32 v62, v63, v70
	v_cvt_pk_bf16_f32 v61, v61, v62
	global_store_dwordx2 v[6:7], v[60:61], off
	v_cvt_pk_bf16_f32 v52, v52, v53
	v_mul_f32_e32 v53, v54, v70
	v_mul_f32_e32 v44, v44, v70
	v_mul_f32_e32 v45, v45, v70
	v_mul_f32_e32 v54, v55, v70
	v_cvt_pk_bf16_f32 v53, v53, v54
	global_store_dwordx2 v[6:7], v[52:53], off offset:32
	v_cvt_pk_bf16_f32 v44, v44, v45
	v_mul_f32_e32 v45, v46, v70
	v_mul_f32_e32 v36, v36, v70
	v_mul_f32_e32 v37, v37, v70
	v_mul_f32_e32 v46, v47, v70
	v_cvt_pk_bf16_f32 v45, v45, v46
	global_store_dwordx2 v[6:7], v[44:45], off offset:64
	v_cvt_pk_bf16_f32 v36, v36, v37
	v_mul_f32_e32 v37, v38, v70
	v_mul_f32_e32 v32, v32, v70
	v_mul_f32_e32 v33, v33, v70
	v_mul_f32_e32 v38, v39, v70
	v_cvt_pk_bf16_f32 v37, v37, v38
	global_store_dwordx2 v[6:7], v[36:37], off offset:96
	v_cvt_pk_bf16_f32 v32, v32, v33
	v_mul_f32_e32 v33, v34, v70
	v_mul_f32_e32 v20, v20, v70
	v_mul_f32_e32 v21, v21, v70
	v_mul_f32_e32 v34, v35, v70
	v_cvt_pk_bf16_f32 v33, v33, v34
	global_store_dwordx2 v[6:7], v[32:33], off offset:128
	v_cvt_pk_bf16_f32 v20, v20, v21
	v_mul_f32_e32 v21, v22, v70
	v_mul_f32_e32 v12, v12, v70
	v_mul_f32_e32 v13, v13, v70
	v_mul_f32_e32 v22, v23, v70
	v_cvt_pk_bf16_f32 v21, v21, v22
	global_store_dwordx2 v[6:7], v[20:21], off offset:160
	v_cvt_pk_bf16_f32 v12, v12, v13
	v_mul_f32_e32 v13, v14, v70
	v_mul_f32_e32 v14, v15, v70
	v_cvt_pk_bf16_f32 v13, v13, v14
	global_store_dwordx2 v[6:7], v[12:13], off offset:192
	v_mul_f32_e32 v12, v64, v70
	v_mul_f32_e32 v13, v65, v70
	v_cvt_pk_bf16_f32 v12, v12, v13
	v_mul_f32_e32 v13, v66, v70
	v_mul_f32_e32 v14, v67, v70
	v_cvt_pk_bf16_f32 v13, v13, v14
	global_store_dwordx2 v[6:7], v[12:13], off offset:224
	ds_bpermute_b32 v6, v68, v81
	s_waitcnt lgkmcnt(0)
	v_add_f32_e32 v6, v81, v6
	ds_bpermute_b32 v7, v69, v6
	s_waitcnt lgkmcnt(0)
	v_add_f32_e32 v6, v6, v7
	v_div_scale_f32 v7, s[8:9], v6, v6, 1.0
	v_rcp_f32_e32 v12, v7
	s_nop 0
	v_fma_f32 v13, -v7, v12, 1.0
	v_fmac_f32_e32 v12, v13, v12
	v_div_scale_f32 v13, vcc, 1.0, v6, 1.0
	v_mul_f32_e32 v14, v13, v12
	v_fma_f32 v15, -v7, v14, v13
	v_fmac_f32_e32 v14, v15, v12
	v_fma_f32 v7, -v7, v14, v13
	v_div_fmas_f32 v7, v7, v12, v14
	v_div_fixup_f32 v12, v7, v6, 1.0
	v_lshlrev_b64 v[6:7], 11, v[150:151]
	v_lshl_add_u64 v[4:5], v[4:5], 0, v[6:7]
	v_mul_f32_e32 v6, v56, v12
	v_mul_f32_e32 v7, v57, v12
	v_cvt_pk_bf16_f32 v6, v6, v7
	v_mul_f32_e32 v7, v58, v12
	v_mul_f32_e32 v13, v59, v12
	v_cvt_pk_bf16_f32 v7, v7, v13
	global_store_dwordx2 v[4:5], v[6:7], off
	v_mul_f32_e32 v6, v48, v12
	v_mul_f32_e32 v7, v49, v12
	v_cvt_pk_bf16_f32 v6, v6, v7
	v_mul_f32_e32 v7, v50, v12
	v_mul_f32_e32 v13, v51, v12
	v_cvt_pk_bf16_f32 v7, v7, v13
	global_store_dwordx2 v[4:5], v[6:7], off offset:32
	v_mul_f32_e32 v6, v40, v12
	v_mul_f32_e32 v7, v41, v12
	v_cvt_pk_bf16_f32 v6, v6, v7
	v_mul_f32_e32 v7, v42, v12
	v_mul_f32_e32 v13, v43, v12
	v_cvt_pk_bf16_f32 v7, v7, v13
	global_store_dwordx2 v[4:5], v[6:7], off offset:64
	v_mul_f32_e32 v6, v28, v12
	v_mul_f32_e32 v7, v29, v12
	v_cvt_pk_bf16_f32 v6, v6, v7
	v_mul_f32_e32 v7, v30, v12
	v_mul_f32_e32 v13, v31, v12
	v_cvt_pk_bf16_f32 v7, v7, v13
	global_store_dwordx2 v[4:5], v[6:7], off offset:96
	v_mul_f32_e32 v6, v24, v12
	v_mul_f32_e32 v7, v25, v12
	v_cvt_pk_bf16_f32 v6, v6, v7
	v_mul_f32_e32 v7, v26, v12
	v_mul_f32_e32 v13, v27, v12
	v_cvt_pk_bf16_f32 v7, v7, v13
	global_store_dwordx2 v[4:5], v[6:7], off offset:128
	v_mul_f32_e32 v6, v16, v12
	v_mul_f32_e32 v7, v17, v12
	v_cvt_pk_bf16_f32 v6, v6, v7
	v_mul_f32_e32 v7, v18, v12
	v_mul_f32_e32 v13, v19, v12
	v_cvt_pk_bf16_f32 v7, v7, v13
	global_store_dwordx2 v[4:5], v[6:7], off offset:160
	v_mul_f32_e32 v6, v8, v12
	v_mul_f32_e32 v7, v9, v12
	v_cvt_pk_bf16_f32 v6, v6, v7
	v_mul_f32_e32 v7, v10, v12
	v_mul_f32_e32 v0, v0, v12
	v_mul_f32_e32 v1, v1, v12
	v_mul_f32_e32 v8, v11, v12
	v_cvt_pk_bf16_f32 v7, v7, v8
	global_store_dwordx2 v[4:5], v[6:7], off offset:192
	v_cvt_pk_bf16_f32 v0, v0, v1
	v_mul_f32_e32 v1, v2, v12
	v_mul_f32_e32 v2, v3, v12
	v_cvt_pk_bf16_f32 v1, v1, v2
	global_store_dwordx2 v[4:5], v[0:1], off offset:224
	s_load_dwordx2 s[8:9], s[0:1], 0x118
	s_waitcnt lgkmcnt(0)
	s_add_i32 s14, s8, s14
	s_cmp_ge_i32 s14, s15
	s_cbranch_scc1 .LBB0_1015

.LBB0_992:
	s_and_b32 s9, s9, 7
	s_mul_i32 s12, s9, 0xc0
	v_add_u32_e32 v152, s10, v180
	s_lshl_b32 s24, s12, 1
	v_lshl_add_u64 v[0:1], v[146:147], 0, s[24:25]
	s_movk_i32 s13, 0xc00
	v_add_u32_e32 v150, 16, v152
	v_mad_i64_i32 v[2:3], s[10:11], v152, s13, v[0:1]
	v_mad_i64_i32 v[0:1], s[10:11], v150, s13, v[0:1]
	global_load_dwordx4 v[104:107], v[2:3], off
	global_load_dwordx4 v[96:99], v[2:3], off offset:64
	global_load_dwordx4 v[88:91], v[2:3], off offset:128
	global_load_dwordx4 v[80:83], v[2:3], off offset:192
	global_load_dwordx4 v[72:75], v[2:3], off offset:256
	global_load_dwordx4 v[64:67], v[2:3], off offset:320
	global_load_dwordx4 v[108:111], v[0:1], off
	global_load_dwordx4 v[100:103], v[0:1], off offset:64
	global_load_dwordx4 v[92:95], v[0:1], off offset:128
	global_load_dwordx4 v[84:87], v[0:1], off offset:192
	global_load_dwordx4 v[76:79], v[0:1], off offset:256
	global_load_dwordx4 v[68:71], v[0:1], off offset:320
	v_add_u32_e32 v0, s12, v145
	v_lshl_add_u32 v158, v0, 1, v182
	v_add_u32_e32 v0, s12, v183
	v_lshl_add_u32 v172, v0, 1, v184
	v_add_u32_e32 v0, s12, v185
	v_lshl_add_u32 v174, v0, 1, v186
	s_lshl_b32 s24, s9, 7
	s_ashr_i32 s9, s8, 31
	s_mul_i32 s10, s8, 0xc00
	v_add_u32_e32 v0, 0, v181
	s_mul_hi_i32 s11, s8, 0xc00
	s_add_u32 s10, s16, s10
	v_readfirstlane_b32 s12, v0
	v_add_u32_e32 v1, 0x2000, v0
	s_addc_u32 s11, s17, s11
	s_mov_b32 m0, s12
	v_readfirstlane_b32 s12, v1
	v_add_u32_e32 v1, 0x4000, v0
	global_load_lds_dwordx4 v158, s[10:11]
	s_mov_b32 m0, s12
	v_readfirstlane_b32 s12, v1
	global_load_lds_dwordx4 v172, s[10:11]
	s_mov_b32 m0, s12
	v_add_u32_e32 v1, s24, v187
	global_load_lds_dwordx4 v174, s[10:11]
	s_lshl_b64 s[10:11], s[8:9], 1
	v_mul_lo_u32 v1, v1, s94
	s_add_u32 s10, s18, s10
	v_add_lshl_u32 v176, v1, v188, 1
	s_addc_u32 s11, s19, s11
	s_mov_b64 s[12:13], exec
	s_cbranch_execz .LBB0_994
	v_add_u32_e32 v1, 0x6000, v0
	s_nop 0
	v_readfirstlane_b32 s9, v1
	s_mov_b32 m0, s9
	s_nop 0
	global_load_lds_dwordx4 v176, s[10:11]
.LBB0_994:
	s_or_b64 exec, exec, s[12:13]
	v_add_u32_e32 v1, s24, v189
	v_mul_lo_u32 v1, v1, s94
	v_add_lshl_u32 v178, v1, v192, 1
	s_mov_b64 s[12:13], exec
	s_cbranch_execz .LBB0_996
	v_add_u32_e32 v1, 0x8000, v0
	s_nop 0
	v_readfirstlane_b32 s9, v1
	s_mov_b32 m0, s9
	s_nop 0
	global_load_lds_dwordx4 v178, s[10:11]

.LBB0_998:
	s_or_b64 exec, exec, s[12:13]
	s_waitcnt vmcnt(0)
	v_mov_b32_e32 v24, v161
	v_mov_b32_e32 v25, v161
	v_mov_b32_e32 v26, v161
	v_mov_b32_e32 v27, v161
	s_lshl_b32 s9, s26, 12
	v_mov_b64_e32 v[30:31], v[26:27]
	v_mov_b64_e32 v[38:39], v[26:27]
	v_mov_b64_e32 v[42:43], v[26:27]
	v_mov_b64_e32 v[46:47], v[26:27]
	v_mov_b64_e32 v[50:51], v[26:27]
	v_mov_b64_e32 v[54:55], v[26:27]
	v_mov_b64_e32 v[58:59], v[26:27]
	v_mov_b64_e32 v[62:63], v[26:27]
	v_mov_b64_e32 v[34:35], v[26:27]
	s_waitcnt vmcnt(0)
	v_mov_b64_e32 v[16:17], v[24:25]
	v_mov_b64_e32 v[20:21], v[24:25]
	v_mov_b64_e32 v[8:9], v[24:25]
	v_mov_b64_e32 v[12:13], v[24:25]
	v_mov_b64_e32 v[0:1], v[24:25]
	v_mov_b64_e32 v[4:5], v[24:25]
	v_ashrrev_i32_e32 v153, 31, v152
	v_ashrrev_i32_e32 v151, 31, v150
	v_mov_b32_e32 v159, v161
	v_mov_b32_e32 v173, v161
	v_mov_b32_e32 v175, v161
	s_add_i32 s13, s9, 0xffffff40
	v_mov_b32_e32 v177, v161
	v_mov_b32_e32 v179, v161
	s_add_i32 s26, s27, 1
	s_add_i32 s27, s8, 64
	s_mov_b32 s29, 0
	v_mov_b32_e32 v154, 0
	v_mov_b32_e32 v203, 0xf149f2ca
	v_mov_b64_e32 v[28:29], v[24:25]
	v_mov_b64_e32 v[36:37], v[24:25]
	v_mov_b64_e32 v[40:41], v[24:25]
	v_mov_b64_e32 v[44:45], v[24:25]
	v_mov_b64_e32 v[48:49], v[24:25]
	v_mov_b64_e32 v[52:53], v[24:25]
	v_mov_b64_e32 v[56:57], v[24:25]
	v_mov_b64_e32 v[60:61], v[24:25]
	v_mov_b32_e32 v162, 0xf149f2ca
	v_mov_b32_e32 v156, 0
	v_mov_b64_e32 v[32:33], v[24:25]
	v_mov_b64_e32 v[18:19], v[26:27]
	v_mov_b64_e32 v[22:23], v[26:27]
	v_mov_b64_e32 v[10:11], v[26:27]
	v_mov_b64_e32 v[14:15], v[26:27]
	v_mov_b64_e32 v[2:3], v[26:27]
	v_mov_b64_e32 v[6:7], v[26:27]
	s_waitcnt lgkmcnt(0)
	s_barrier
	v_mul_f32_e32 v157, 0xbdd53b94, v162
	v_mul_f32_e32 v155, 0xbdd53b94, v203
	s_mov_b32 s2, 0
	s_mov_b32 s3, 0
	v_readfirstlane_b32 s4, v181
	s_bitcmp1_b32 s4, 12
	s_cbranch_scc1 .Lattn_b_top
.LBB0_999:
	s_add_i32 s28, s29, 1
	s_cmp_lt_u32 s29, 3
	s_cselect_b32 s8, s27, s13
	s_mul_i32 s10, s8, 0xc00
	s_mul_hi_i32 s11, s8, 0xc00
	s_add_u32 s10, s16, s10
	s_addc_u32 s11, s17, s11
	s_ashr_i32 vcc_hi, s8, 31
	s_mov_b32 vcc_lo, s8
	s_lshl_b64 vcc, vcc, 1
	s_add_u32 vcc_lo, s18, vcc_lo
	s_addc_u32 vcc_hi, s19, vcc_hi
	s_bitcmp1_b32 s28, 0
	s_cselect_b32 s12, 0xa800, 0
	v_readfirstlane_b32 s30, v181
	s_add_i32 s5, s2, 0xa800
	s_cmp_eq_u32 s5, 0x1f800
	s_cselect_b32 s5, 0, s5
	s_add_i32 s9, s30, s5
	s_addk_i32 s9, 0x6000
	s_add_i32 s30, s30, s12
	s_bitcmp1_b32 s29, 0
	s_cselect_b32 s8, 0xa800, 0
	v_add_u32_e32 v116, s8, v198
	ds_read_b128 v[116:119], v116
	v_add_u32_e32 v124, s8, v199
	ds_read_b128 v[124:127], v124
	v_add_u32_e32 v128, s8, v200
	ds_read_b128 v[128:131], v128
	v_add_u32_e32 v136, s8, v201
	ds_read_b128 v[136:139], v136
	v_add_u32_e32 v132, s8, v225
	ds_read_b128 v[132:135], v132
	v_add_u32_e32 v140, s8, v226
	ds_read_b128 v[140:143], v140
	s_waitcnt lgkmcnt(5)
	v_mfma_f32_16x16x32_bf16 v[112:115], v[116:119], v[104:107], 0
	v_mfma_f32_16x16x32_bf16 v[120:123], v[116:119], v[108:111], 0
	v_add_u32_e32 v204, s8, v234
	ds_read_b128 v[204:207], v204
	s_waitcnt lgkmcnt(5)
	v_mfma_f32_16x16x32_bf16 v[112:115], v[124:127], v[96:99], v[112:115]
	v_mfma_f32_16x16x32_bf16 v[120:123], v[124:127], v[100:103], v[120:123]
	v_add_u32_e32 v208, s8, v235
	ds_read_b128 v[208:211], v208
	s_add_i32 m0, s30, 0x0
	s_waitcnt lgkmcnt(5)
	v_mfma_f32_16x16x32_bf16 v[112:115], v[128:131], v[88:91], v[112:115]
	v_mfma_f32_16x16x32_bf16 v[120:123], v[128:131], v[92:95], v[120:123]
	global_load_lds_dwordx4 v158, s[10:11]
	v_add_u32_e32 v128, s8, v236
	ds_read_b128 v[128:131], v128
	s_waitcnt lgkmcnt(5)
	v_mfma_f32_16x16x32_bf16 v[112:115], v[136:139], v[80:83], v[112:115]
	v_mfma_f32_16x16x32_bf16 v[120:123], v[136:139], v[84:87], v[120:123]
	v_add_u32_e32 v136, s8, v237
	ds_read_b128 v[136:139], v136
	s_waitcnt lgkmcnt(5)
	v_mfma_f32_16x16x32_bf16 v[112:115], v[132:135], v[72:75], v[112:115]
	v_mfma_f32_16x16x32_bf16 v[120:123], v[132:135], v[76:79], v[120:123]
	v_add_u32_e32 v132, s8, v238
	ds_read_b128 v[132:135], v132
	s_add_i32 m0, s30, 0x2000
	s_waitcnt lgkmcnt(5)
	v_mfma_f32_16x16x32_bf16 v[112:115], v[140:143], v[64:67], v[112:115]
	v_mfma_f32_16x16x32_bf16 v[120:123], v[140:143], v[68:71], v[120:123]
	global_load_lds_dwordx4 v172, s[10:11]
	v_add_u32_e32 v140, s8, v239
	ds_read_b128 v[140:143], v140
	s_waitcnt lgkmcnt(5)
	v_mfma_f32_16x16x32_bf16 v[116:119], v[204:207], v[104:107], 0
	v_mfma_f32_16x16x32_bf16 v[124:127], v[204:207], v[108:111], 0
	v_add_u32_e32 v204, s8, v240
	ds_read_b128 v[204:207], v204
	s_waitcnt lgkmcnt(5)
	v_mfma_f32_16x16x32_bf16 v[116:119], v[208:211], v[96:99], v[116:119]
	v_mfma_f32_16x16x32_bf16 v[124:127], v[208:211], v[100:103], v[124:127]
	v_add_u32_e32 v208, s8, v241
	ds_read_b128 v[208:211], v208
	s_add_i32 m0, s30, 0x4000
	s_waitcnt lgkmcnt(5)
	v_mfma_f32_16x16x32_bf16 v[116:119], v[128:131], v[88:91], v[116:119]
	v_mfma_f32_16x16x32_bf16 v[124:127], v[128:131], v[92:95], v[124:127]
	global_load_lds_dwordx4 v174, s[10:11]
	s_waitcnt lgkmcnt(4)
	v_mfma_f32_16x16x32_bf16 v[116:119], v[136:139], v[80:83], v[116:119]
	v_mfma_f32_16x16x32_bf16 v[124:127], v[136:139], v[84:87], v[124:127]
	s_waitcnt lgkmcnt(3)
	v_mfma_f32_16x16x32_bf16 v[116:119], v[132:135], v[72:75], v[116:119]
	v_mfma_f32_16x16x32_bf16 v[124:127], v[132:135], v[76:79], v[124:127]
	v_add_u32_e32 v132, s8, v242
	ds_read_b128 v[132:135], v132
	s_add_i32 m0, s9, 0x0
	s_waitcnt lgkmcnt(3)
	v_mfma_f32_16x16x32_bf16 v[116:119], v[140:143], v[64:67], v[116:119]
	v_mfma_f32_16x16x32_bf16 v[124:127], v[140:143], v[68:71], v[124:127]
	global_load_lds_dwordx4 v176, vcc
	v_add_u32_e32 v140, s8, v243
	ds_read_b128 v[140:143], v140
	s_waitcnt lgkmcnt(3)
	v_mfma_f32_16x16x32_bf16 v[136:139], v[204:207], v[104:107], 0
	v_mfma_f32_16x16x32_bf16 v[128:131], v[204:207], v[108:111], 0
	v_add_u32_e32 v204, s8, v244
	ds_read_b128 v[204:207], v204
	s_waitcnt lgkmcnt(3)
	v_mfma_f32_16x16x32_bf16 v[136:139], v[208:211], v[96:99], v[136:139]
	v_mfma_f32_16x16x32_bf16 v[128:131], v[208:211], v[100:103], v[128:131]
	v_add_u32_e32 v208, s8, v245
	ds_read_b128 v[208:211], v208
	s_add_i32 m0, s9, 0x2000
	s_waitcnt lgkmcnt(3)
	v_mfma_f32_16x16x32_bf16 v[136:139], v[132:135], v[88:91], v[136:139]
	v_mfma_f32_16x16x32_bf16 v[128:131], v[132:135], v[92:95], v[128:131]
	global_load_lds_dwordx4 v178, vcc
	s_waitcnt lgkmcnt(2)
	v_mfma_f32_16x16x32_bf16 v[136:139], v[140:143], v[80:83], v[136:139]
	v_mfma_f32_16x16x32_bf16 v[128:131], v[140:143], v[84:87], v[128:131]
	s_waitcnt lgkmcnt(1)
	v_mfma_f32_16x16x32_bf16 v[136:139], v[204:207], v[72:75], v[136:139]
	v_mfma_f32_16x16x32_bf16 v[128:131], v[204:207], v[76:79], v[128:131]
	v_add_u32_e32 v204, s8, v246
	ds_read_b128 v[204:207], v204
	s_waitcnt lgkmcnt(1)
	v_mfma_f32_16x16x32_bf16 v[136:139], v[208:211], v[64:67], v[136:139]
	v_mfma_f32_16x16x32_bf16 v[128:131], v[208:211], v[68:71], v[128:131]
	s_cmp_lg_u64 s[6:7], 0
	s_cbranch_scc0 .Lat_v2skip_a
	s_add_i32 m0, s9, 0x4000
	s_nop 0
	global_load_lds_dwordx4 v160, vcc

.Lattn_pv:
	v_add3_u32 v230, s2, v144, v202
	ds_read_b64 v[128:129], v230 offset:24576
	ds_read_b64 v[130:131], v230 offset:24608
	ds_read_b64 v[132:133], v230 offset:24640
	ds_read_b64 v[134:135], v230 offset:24672
	ds_read_b64 v[136:137], v230 offset:26880
	ds_read_b64 v[138:139], v230 offset:26912
	ds_read_b64 v[140:141], v230 offset:26944
	ds_read_b64 v[142:143], v230 offset:26976
	ds_read_b64 v[204:205], v230 offset:29184
	ds_read_b64 v[206:207], v230 offset:29216
	ds_read_b64 v[208:209], v230 offset:29248
	ds_read_b64 v[210:211], v230 offset:29280
	s_waitcnt lgkmcnt(10)
	v_mfma_f32_16x16x32_bf16 v[60:63], v[128:131], v[116:119], v[60:63]
	v_mfma_f32_16x16x32_bf16 v[56:59], v[128:131], v[124:127], v[56:59]
	ds_read_b64 v[128:129], v230 offset:31488
	ds_read_b64 v[130:131], v230 offset:31520
	s_waitcnt lgkmcnt(10)
	v_mfma_f32_16x16x32_bf16 v[60:63], v[132:135], v[112:115], v[60:63]
	v_mfma_f32_16x16x32_bf16 v[56:59], v[132:135], v[120:123], v[56:59]
	ds_read_b64 v[132:133], v230 offset:31552
	ds_read_b64 v[134:135], v230 offset:31584
	s_waitcnt lgkmcnt(10)
	v_mfma_f32_16x16x32_bf16 v[52:55], v[136:139], v[116:119], v[52:55]
	v_mfma_f32_16x16x32_bf16 v[48:51], v[136:139], v[124:127], v[48:51]
	ds_read_b64 v[136:137], v230 offset:33792
	ds_read_b64 v[138:139], v230 offset:33824
	s_waitcnt lgkmcnt(10)
	v_mfma_f32_16x16x32_bf16 v[52:55], v[140:143], v[112:115], v[52:55]
	v_mfma_f32_16x16x32_bf16 v[48:51], v[140:143], v[120:123], v[48:51]
	ds_read_b64 v[140:141], v230 offset:33856
	ds_read_b64 v[142:143], v230 offset:33888
	s_waitcnt lgkmcnt(10)
	v_mfma_f32_16x16x32_bf16 v[44:47], v[204:207], v[116:119], v[44:47]
	v_mfma_f32_16x16x32_bf16 v[40:43], v[204:207], v[124:127], v[40:43]
	ds_read_b64 v[204:205], v230 offset:36096
	ds_read_b64 v[206:207], v230 offset:36128
	s_waitcnt lgkmcnt(10)
	v_mfma_f32_16x16x32_bf16 v[44:47], v[208:211], v[112:115], v[44:47]
	v_mfma_f32_16x16x32_bf16 v[40:43], v[208:211], v[120:123], v[40:43]
	ds_read_b64 v[208:209], v230 offset:36160
	ds_read_b64 v[210:211], v230 offset:36192
	s_waitcnt lgkmcnt(10)
	v_mfma_f32_16x16x32_bf16 v[36:39], v[128:131], v[116:119], v[36:39]
	v_mfma_f32_16x16x32_bf16 v[28:31], v[128:131], v[124:127], v[28:31]
	ds_read_b64 v[128:129], v230 offset:38400
	ds_read_b64 v[130:131], v230 offset:38432
	s_waitcnt lgkmcnt(10)
	v_mfma_f32_16x16x32_bf16 v[36:39], v[132:135], v[112:115], v[36:39]
	v_mfma_f32_16x16x32_bf16 v[28:31], v[132:135], v[120:123], v[28:31]
	ds_read_b64 v[132:133], v230 offset:38464
	ds_read_b64 v[134:135], v230 offset:38496
	s_waitcnt lgkmcnt(10)
	v_mfma_f32_16x16x32_bf16 v[24:27], v[136:139], v[116:119], v[24:27]
	v_mfma_f32_16x16x32_bf16 v[32:35], v[136:139], v[124:127], v[32:35]
	ds_read_b64 v[136:137], v230 offset:40704
	ds_read_b64 v[138:139], v230 offset:40736
	s_waitcnt lgkmcnt(10)
	v_mfma_f32_16x16x32_bf16 v[24:27], v[140:143], v[112:115], v[24:27]
	v_mfma_f32_16x16x32_bf16 v[32:35], v[140:143], v[120:123], v[32:35]
	ds_read_b64 v[140:141], v230 offset:40768
	ds_read_b64 v[142:143], v230 offset:40800
	s_waitcnt lgkmcnt(10)
	v_mfma_f32_16x16x32_bf16 v[16:19], v[204:207], v[116:119], v[16:19]
	v_mfma_f32_16x16x32_bf16 v[20:23], v[204:207], v[124:127], v[20:23]
	s_waitcnt lgkmcnt(8)
	v_mfma_f32_16x16x32_bf16 v[16:19], v[208:211], v[112:115], v[16:19]
	v_mfma_f32_16x16x32_bf16 v[20:23], v[208:211], v[120:123], v[20:23]
	s_waitcnt lgkmcnt(6)
	v_mfma_f32_16x16x32_bf16 v[8:11], v[128:131], v[116:119], v[8:11]
	v_mfma_f32_16x16x32_bf16 v[12:15], v[128:131], v[124:127], v[12:15]
	s_waitcnt lgkmcnt(4)
	v_mfma_f32_16x16x32_bf16 v[8:11], v[132:135], v[112:115], v[8:11]
	v_mfma_f32_16x16x32_bf16 v[12:15], v[132:135], v[120:123], v[12:15]
	s_waitcnt lgkmcnt(2)
	v_mfma_f32_16x16x32_bf16 v[0:3], v[136:139], v[116:119], v[0:3]
	v_mfma_f32_16x16x32_bf16 v[4:7], v[136:139], v[124:127], v[4:7]
	s_waitcnt lgkmcnt(0)
	v_mfma_f32_16x16x32_bf16 v[0:3], v[140:143], v[112:115], v[0:3]
	v_mfma_f32_16x16x32_bf16 v[4:7], v[140:143], v[120:123], v[4:7]
	s_add_i32 s13, s13, 64
	s_add_i32 s27, s27, 64
	s_mov_b32 s2, s5
	s_cmp_eq_u32 s26, s28
	s_waitcnt vmcnt(0) lgkmcnt(0)
	s_barrier
	s_cbranch_scc1 .LBB0_1011
	s_mov_b32 s29, s28
	s_branch .LBB0_999

.Lattn_b_top:
	s_add_i32 s28, s29, 1
	s_cmp_eq_u32 s29, 0
	s_cbranch_scc1 .Lattn_b_qk
	v_add3_u32 v230, s3, v144, v202
	ds_read_b64 v[128:129], v230 offset:24576
	ds_read_b64 v[130:131], v230 offset:24608
	ds_read_b64 v[132:133], v230 offset:24640
	ds_read_b64 v[134:135], v230 offset:24672
	ds_read_b64 v[136:137], v230 offset:26880
	ds_read_b64 v[138:139], v230 offset:26912
	ds_read_b64 v[140:141], v230 offset:26944
	ds_read_b64 v[142:143], v230 offset:26976
	ds_read_b64 v[204:205], v230 offset:29184
	ds_read_b64 v[206:207], v230 offset:29216
	ds_read_b64 v[208:209], v230 offset:29248
	ds_read_b64 v[210:211], v230 offset:29280
	s_waitcnt lgkmcnt(10)
	v_mfma_f32_16x16x32_bf16 v[60:63], v[128:131], v[116:119], v[60:63]
	v_mfma_f32_16x16x32_bf16 v[56:59], v[128:131], v[124:127], v[56:59]
	ds_read_b64 v[128:129], v230 offset:31488
	ds_read_b64 v[130:131], v230 offset:31520
	s_waitcnt lgkmcnt(10)
	v_mfma_f32_16x16x32_bf16 v[60:63], v[132:135], v[112:115], v[60:63]
	v_mfma_f32_16x16x32_bf16 v[56:59], v[132:135], v[120:123], v[56:59]
	ds_read_b64 v[132:133], v230 offset:31552
	ds_read_b64 v[134:135], v230 offset:31584
	s_waitcnt lgkmcnt(10)
	v_mfma_f32_16x16x32_bf16 v[52:55], v[136:139], v[116:119], v[52:55]
	v_mfma_f32_16x16x32_bf16 v[48:51], v[136:139], v[124:127], v[48:51]
	ds_read_b64 v[136:137], v230 offset:33792
	ds_read_b64 v[138:139], v230 offset:33824
	s_waitcnt lgkmcnt(10)
	v_mfma_f32_16x16x32_bf16 v[52:55], v[140:143], v[112:115], v[52:55]
	v_mfma_f32_16x16x32_bf16 v[48:51], v[140:143], v[120:123], v[48:51]
	ds_read_b64 v[140:141], v230 offset:33856
	ds_read_b64 v[142:143], v230 offset:33888
	s_waitcnt lgkmcnt(10)
	v_mfma_f32_16x16x32_bf16 v[44:47], v[204:207], v[116:119], v[44:47]
	v_mfma_f32_16x16x32_bf16 v[40:43], v[204:207], v[124:127], v[40:43]
	ds_read_b64 v[204:205], v230 offset:36096
	ds_read_b64 v[206:207], v230 offset:36128
	s_waitcnt lgkmcnt(10)
	v_mfma_f32_16x16x32_bf16 v[44:47], v[208:211], v[112:115], v[44:47]
	v_mfma_f32_16x16x32_bf16 v[40:43], v[208:211], v[120:123], v[40:43]
	ds_read_b64 v[208:209], v230 offset:36160
	ds_read_b64 v[210:211], v230 offset:36192
	s_waitcnt lgkmcnt(10)
	v_mfma_f32_16x16x32_bf16 v[36:39], v[128:131], v[116:119], v[36:39]
	v_mfma_f32_16x16x32_bf16 v[28:31], v[128:131], v[124:127], v[28:31]
	ds_read_b64 v[128:129], v230 offset:38400
	ds_read_b64 v[130:131], v230 offset:38432
	s_waitcnt lgkmcnt(10)
	v_mfma_f32_16x16x32_bf16 v[36:39], v[132:135], v[112:115], v[36:39]
	v_mfma_f32_16x16x32_bf16 v[28:31], v[132:135], v[120:123], v[28:31]
	ds_read_b64 v[132:133], v230 offset:38464
	ds_read_b64 v[134:135], v230 offset:38496
	s_waitcnt lgkmcnt(10)
	v_mfma_f32_16x16x32_bf16 v[24:27], v[136:139], v[116:119], v[24:27]
	v_mfma_f32_16x16x32_bf16 v[32:35], v[136:139], v[124:127], v[32:35]
	ds_read_b64 v[136:137], v230 offset:40704
	ds_read_b64 v[138:139], v230 offset:40736
	s_waitcnt lgkmcnt(10)
	v_mfma_f32_16x16x32_bf16 v[24:27], v[140:143], v[112:115], v[24:27]
	v_mfma_f32_16x16x32_bf16 v[32:35], v[140:143], v[120:123], v[32:35]
	ds_read_b64 v[140:141], v230 offset:40768
	ds_read_b64 v[142:143], v230 offset:40800
	s_waitcnt lgkmcnt(10)
	v_mfma_f32_16x16x32_bf16 v[16:19], v[204:207], v[116:119], v[16:19]
	v_mfma_f32_16x16x32_bf16 v[20:23], v[204:207], v[124:127], v[20:23]
	s_waitcnt lgkmcnt(8)
	v_mfma_f32_16x16x32_bf16 v[16:19], v[208:211], v[112:115], v[16:19]
	v_mfma_f32_16x16x32_bf16 v[20:23], v[208:211], v[120:123], v[20:23]
	s_waitcnt lgkmcnt(6)
	v_mfma_f32_16x16x32_bf16 v[8:11], v[128:131], v[116:119], v[8:11]
	v_mfma_f32_16x16x32_bf16 v[12:15], v[128:131], v[124:127], v[12:15]
	s_waitcnt lgkmcnt(4)
	v_mfma_f32_16x16x32_bf16 v[8:11], v[132:135], v[112:115], v[8:11]
	v_mfma_f32_16x16x32_bf16 v[12:15], v[132:135], v[120:123], v[12:15]
	s_waitcnt lgkmcnt(2)
	v_mfma_f32_16x16x32_bf16 v[0:3], v[136:139], v[116:119], v[0:3]
	v_mfma_f32_16x16x32_bf16 v[4:7], v[136:139], v[124:127], v[4:7]
	s_waitcnt lgkmcnt(0)
	v_mfma_f32_16x16x32_bf16 v[0:3], v[140:143], v[112:115], v[0:3]
	v_mfma_f32_16x16x32_bf16 v[4:7], v[140:143], v[120:123], v[4:7]
.Lattn_b_qk:
	s_cmp_lt_u32 s29, 3
	s_cselect_b32 s8, s27, s13
	s_mul_i32 s10, s8, 0xc00
	s_mul_hi_i32 s11, s8, 0xc00
	s_add_u32 s10, s16, s10
	s_addc_u32 s11, s17, s11
	s_ashr_i32 vcc_hi, s8, 31
	s_mov_b32 vcc_lo, s8
	s_lshl_b64 vcc, vcc, 1
	s_add_u32 vcc_lo, s18, vcc_lo
	s_addc_u32 vcc_hi, s19, vcc_hi
	s_bitcmp1_b32 s28, 0
	s_cselect_b32 s12, 0xa800, 0
	v_readfirstlane_b32 s30, v181
	s_add_i32 s5, s2, 0xa800
	s_cmp_eq_u32 s5, 0x1f800
	s_cselect_b32 s5, 0, s5
	s_add_i32 s9, s30, s5
	s_addk_i32 s9, 0x6000
	s_add_i32 s30, s30, s12
	s_bitcmp1_b32 s29, 0
	s_cselect_b32 s8, 0xa800, 0
	v_add_u32_e32 v116, s8, v198
	ds_read_b128 v[116:119], v116
	v_add_u32_e32 v124, s8, v199
	ds_read_b128 v[124:127], v124
	v_add_u32_e32 v128, s8, v200
	ds_read_b128 v[128:131], v128
	v_add_u32_e32 v136, s8, v201
	ds_read_b128 v[136:139], v136
	v_add_u32_e32 v132, s8, v225
	ds_read_b128 v[132:135], v132
	v_add_u32_e32 v140, s8, v226
	ds_read_b128 v[140:143], v140
	s_waitcnt lgkmcnt(5)
	v_mfma_f32_16x16x32_bf16 v[112:115], v[116:119], v[104:107], 0
	v_mfma_f32_16x16x32_bf16 v[120:123], v[116:119], v[108:111], 0
	v_add_u32_e32 v204, s8, v234
	ds_read_b128 v[204:207], v204
	s_waitcnt lgkmcnt(5)
	v_mfma_f32_16x16x32_bf16 v[112:115], v[124:127], v[96:99], v[112:115]
	v_mfma_f32_16x16x32_bf16 v[120:123], v[124:127], v[100:103], v[120:123]
	v_add_u32_e32 v208, s8, v235
	ds_read_b128 v[208:211], v208
	s_add_i32 m0, s30, 0x0
	s_waitcnt lgkmcnt(5)
	v_mfma_f32_16x16x32_bf16 v[112:115], v[128:131], v[88:91], v[112:115]
	v_mfma_f32_16x16x32_bf16 v[120:123], v[128:131], v[92:95], v[120:123]
	global_load_lds_dwordx4 v158, s[10:11]
	v_add_u32_e32 v128, s8, v236
	ds_read_b128 v[128:131], v128
	s_waitcnt lgkmcnt(5)
	v_mfma_f32_16x16x32_bf16 v[112:115], v[136:139], v[80:83], v[112:115]
	v_mfma_f32_16x16x32_bf16 v[120:123], v[136:139], v[84:87], v[120:123]
	v_add_u32_e32 v136, s8, v237
	ds_read_b128 v[136:139], v136
	s_waitcnt lgkmcnt(5)
	v_mfma_f32_16x16x32_bf16 v[112:115], v[132:135], v[72:75], v[112:115]
	v_mfma_f32_16x16x32_bf16 v[120:123], v[132:135], v[76:79], v[120:123]
	v_add_u32_e32 v132, s8, v238
	ds_read_b128 v[132:135], v132
	s_add_i32 m0, s30, 0x2000
	s_waitcnt lgkmcnt(5)
	v_mfma_f32_16x16x32_bf16 v[112:115], v[140:143], v[64:67], v[112:115]
	v_mfma_f32_16x16x32_bf16 v[120:123], v[140:143], v[68:71], v[120:123]
	global_load_lds_dwordx4 v172, s[10:11]
	v_add_u32_e32 v140, s8, v239
	ds_read_b128 v[140:143], v140
	s_waitcnt lgkmcnt(5)
	v_mfma_f32_16x16x32_bf16 v[116:119], v[204:207], v[104:107], 0
	v_mfma_f32_16x16x32_bf16 v[124:127], v[204:207], v[108:111], 0
	v_add_u32_e32 v204, s8, v240
	ds_read_b128 v[204:207], v204
	s_waitcnt lgkmcnt(5)
	v_mfma_f32_16x16x32_bf16 v[116:119], v[208:211], v[96:99], v[116:119]
	v_mfma_f32_16x16x32_bf16 v[124:127], v[208:211], v[100:103], v[124:127]
	v_add_u32_e32 v208, s8, v241
	ds_read_b128 v[208:211], v208
	s_add_i32 m0, s30, 0x4000
	s_waitcnt lgkmcnt(5)
	v_mfma_f32_16x16x32_bf16 v[116:119], v[128:131], v[88:91], v[116:119]
	v_mfma_f32_16x16x32_bf16 v[124:127], v[128:131], v[92:95], v[124:127]
	global_load_lds_dwordx4 v174, s[10:11]
	s_waitcnt lgkmcnt(4)
	v_mfma_f32_16x16x32_bf16 v[116:119], v[136:139], v[80:83], v[116:119]
	v_mfma_f32_16x16x32_bf16 v[124:127], v[136:139], v[84:87], v[124:127]
	s_waitcnt lgkmcnt(3)
	v_mfma_f32_16x16x32_bf16 v[116:119], v[132:135], v[72:75], v[116:119]
	v_mfma_f32_16x16x32_bf16 v[124:127], v[132:135], v[76:79], v[124:127]
	v_add_u32_e32 v132, s8, v242
	ds_read_b128 v[132:135], v132
	s_add_i32 m0, s9, 0x0
	s_waitcnt lgkmcnt(3)
	v_mfma_f32_16x16x32_bf16 v[116:119], v[140:143], v[64:67], v[116:119]
	v_mfma_f32_16x16x32_bf16 v[124:127], v[140:143], v[68:71], v[124:127]
	global_load_lds_dwordx4 v176, vcc
	v_add_u32_e32 v140, s8, v243
	ds_read_b128 v[140:143], v140
	s_waitcnt lgkmcnt(3)
	v_mfma_f32_16x16x32_bf16 v[136:139], v[204:207], v[104:107], 0
	v_mfma_f32_16x16x32_bf16 v[128:131], v[204:207], v[108:111], 0
	v_add_u32_e32 v204, s8, v244
	ds_read_b128 v[204:207], v204
	s_waitcnt lgkmcnt(3)
	v_mfma_f32_16x16x32_bf16 v[136:139], v[208:211], v[96:99], v[136:139]
	v_mfma_f32_16x16x32_bf16 v[128:131], v[208:211], v[100:103], v[128:131]
	v_add_u32_e32 v208, s8, v245
	ds_read_b128 v[208:211], v208
	s_add_i32 m0, s9, 0x2000
	s_waitcnt lgkmcnt(3)
	v_mfma_f32_16x16x32_bf16 v[136:139], v[132:135], v[88:91], v[136:139]
	v_mfma_f32_16x16x32_bf16 v[128:131], v[132:135], v[92:95], v[128:131]
	global_load_lds_dwordx4 v178, vcc
	s_waitcnt lgkmcnt(2)
	v_mfma_f32_16x16x32_bf16 v[136:139], v[140:143], v[80:83], v[136:139]
	v_mfma_f32_16x16x32_bf16 v[128:131], v[140:143], v[84:87], v[128:131]
	s_waitcnt lgkmcnt(1)
	v_mfma_f32_16x16x32_bf16 v[136:139], v[204:207], v[72:75], v[136:139]
	v_mfma_f32_16x16x32_bf16 v[128:131], v[204:207], v[76:79], v[128:131]
	v_add_u32_e32 v204, s8, v246
	ds_read_b128 v[204:207], v204
	s_waitcnt lgkmcnt(1)
	v_mfma_f32_16x16x32_bf16 v[136:139], v[208:211], v[64:67], v[136:139]
	v_mfma_f32_16x16x32_bf16 v[128:131], v[208:211], v[68:71], v[128:131]
	s_cmp_lg_u64 s[6:7], 0
	s_cbranch_scc0 .Lat_v2skip_b
	s_add_i32 m0, s9, 0x4000
	s_nop 0
	global_load_lds_dwordx4 v160, vcc

.Lattn_b_tail:
	s_add_i32 s13, s13, 64
	s_add_i32 s27, s27, 64
	s_mov_b32 s3, s2
	s_mov_b32 s2, s5
	s_cmp_eq_u32 s26, s28
	s_waitcnt vmcnt(0) lgkmcnt(0)
	s_barrier
	s_cbranch_scc1 .Lattn_b_last
	s_mov_b32 s29, s28
	s_branch .Lattn_b_top
.Lattn_b_last:
	v_add3_u32 v230, s3, v144, v202
	ds_read_b64 v[128:129], v230 offset:24576
	ds_read_b64 v[130:131], v230 offset:24608
	ds_read_b64 v[132:133], v230 offset:24640
	ds_read_b64 v[134:135], v230 offset:24672
	ds_read_b64 v[136:137], v230 offset:26880
	ds_read_b64 v[138:139], v230 offset:26912
	ds_read_b64 v[140:141], v230 offset:26944
	ds_read_b64 v[142:143], v230 offset:26976
	ds_read_b64 v[204:205], v230 offset:29184
	ds_read_b64 v[206:207], v230 offset:29216
	ds_read_b64 v[208:209], v230 offset:29248
	ds_read_b64 v[210:211], v230 offset:29280
	s_waitcnt lgkmcnt(10)
	v_mfma_f32_16x16x32_bf16 v[60:63], v[128:131], v[116:119], v[60:63]
	v_mfma_f32_16x16x32_bf16 v[56:59], v[128:131], v[124:127], v[56:59]
	ds_read_b64 v[128:129], v230 offset:31488
	ds_read_b64 v[130:131], v230 offset:31520
	s_waitcnt lgkmcnt(10)
	v_mfma_f32_16x16x32_bf16 v[60:63], v[132:135], v[112:115], v[60:63]
	v_mfma_f32_16x16x32_bf16 v[56:59], v[132:135], v[120:123], v[56:59]
	ds_read_b64 v[132:133], v230 offset:31552
	ds_read_b64 v[134:135], v230 offset:31584
	s_waitcnt lgkmcnt(10)
	v_mfma_f32_16x16x32_bf16 v[52:55], v[136:139], v[116:119], v[52:55]
	v_mfma_f32_16x16x32_bf16 v[48:51], v[136:139], v[124:127], v[48:51]
	ds_read_b64 v[136:137], v230 offset:33792
	ds_read_b64 v[138:139], v230 offset:33824
	s_waitcnt lgkmcnt(10)
	v_mfma_f32_16x16x32_bf16 v[52:55], v[140:143], v[112:115], v[52:55]
	v_mfma_f32_16x16x32_bf16 v[48:51], v[140:143], v[120:123], v[48:51]
	ds_read_b64 v[140:141], v230 offset:33856
	ds_read_b64 v[142:143], v230 offset:33888
	s_waitcnt lgkmcnt(10)
	v_mfma_f32_16x16x32_bf16 v[44:47], v[204:207], v[116:119], v[44:47]
	v_mfma_f32_16x16x32_bf16 v[40:43], v[204:207], v[124:127], v[40:43]
	ds_read_b64 v[204:205], v230 offset:36096
	ds_read_b64 v[206:207], v230 offset:36128
	s_waitcnt lgkmcnt(10)
	v_mfma_f32_16x16x32_bf16 v[44:47], v[208:211], v[112:115], v[44:47]
	v_mfma_f32_16x16x32_bf16 v[40:43], v[208:211], v[120:123], v[40:43]
	ds_read_b64 v[208:209], v230 offset:36160
	ds_read_b64 v[210:211], v230 offset:36192
	s_waitcnt lgkmcnt(10)
	v_mfma_f32_16x16x32_bf16 v[36:39], v[128:131], v[116:119], v[36:39]
	v_mfma_f32_16x16x32_bf16 v[28:31], v[128:131], v[124:127], v[28:31]
	ds_read_b64 v[128:129], v230 offset:38400
	ds_read_b64 v[130:131], v230 offset:38432
	s_waitcnt lgkmcnt(10)
	v_mfma_f32_16x16x32_bf16 v[36:39], v[132:135], v[112:115], v[36:39]
	v_mfma_f32_16x16x32_bf16 v[28:31], v[132:135], v[120:123], v[28:31]
	ds_read_b64 v[132:133], v230 offset:38464
	ds_read_b64 v[134:135], v230 offset:38496
	s_waitcnt lgkmcnt(10)
	v_mfma_f32_16x16x32_bf16 v[24:27], v[136:139], v[116:119], v[24:27]
	v_mfma_f32_16x16x32_bf16 v[32:35], v[136:139], v[124:127], v[32:35]
	ds_read_b64 v[136:137], v230 offset:40704
	ds_read_b64 v[138:139], v230 offset:40736
	s_waitcnt lgkmcnt(10)
	v_mfma_f32_16x16x32_bf16 v[24:27], v[140:143], v[112:115], v[24:27]
	v_mfma_f32_16x16x32_bf16 v[32:35], v[140:143], v[120:123], v[32:35]
	ds_read_b64 v[140:141], v230 offset:40768
	ds_read_b64 v[142:143], v230 offset:40800
	s_waitcnt lgkmcnt(10)
	v_mfma_f32_16x16x32_bf16 v[16:19], v[204:207], v[116:119], v[16:19]
	v_mfma_f32_16x16x32_bf16 v[20:23], v[204:207], v[124:127], v[20:23]
	s_waitcnt lgkmcnt(8)
	v_mfma_f32_16x16x32_bf16 v[16:19], v[208:211], v[112:115], v[16:19]
	v_mfma_f32_16x16x32_bf16 v[20:23], v[208:211], v[120:123], v[20:23]
	s_waitcnt lgkmcnt(6)
	v_mfma_f32_16x16x32_bf16 v[8:11], v[128:131], v[116:119], v[8:11]
	v_mfma_f32_16x16x32_bf16 v[12:15], v[128:131], v[124:127], v[12:15]
	s_waitcnt lgkmcnt(4)
	v_mfma_f32_16x16x32_bf16 v[8:11], v[132:135], v[112:115], v[8:11]
	v_mfma_f32_16x16x32_bf16 v[12:15], v[132:135], v[120:123], v[12:15]
	s_waitcnt lgkmcnt(2)
	v_mfma_f32_16x16x32_bf16 v[0:3], v[136:139], v[116:119], v[0:3]
	v_mfma_f32_16x16x32_bf16 v[4:7], v[136:139], v[124:127], v[4:7]
	s_waitcnt lgkmcnt(0)
	v_mfma_f32_16x16x32_bf16 v[0:3], v[140:143], v[112:115], v[0:3]
	v_mfma_f32_16x16x32_bf16 v[4:7], v[140:143], v[120:123], v[4:7]
	s_branch .LBB0_1011
